# QKV/GU: phase-start row-stat loads issued as one batch; per-tile post-epilogue wait counted (vmcnt 8/16) and the vmcnt(0) in the GU K-loop preheader removed so epilogue stores drain behind the next ti
# baseline (speedup 1.0000x reference)
; #define PG8_RTAB_FILL() do { if constexpr (Epi::ROWSCALE) { if (tid < 256) rtab[(ui & 1) * 256 + tid] = row_rstd(E.part, cur.pm * 256 + tid); } } while (0)
; __device__ __forceinline__ float row_rstd(const float* part, int row) {
;     const f32x4* p = (const f32x4*)(part + (size_t)row * NPART); f32x4 s = p[0];
; #pragma unroll
;     for (int i = 1; i < NPART / 4; ++i) s += p[i];
;     const float t = (s.x + s.y) + (s.z + s.w);
;     return __builtin_amdgcn_rsqf(t * (1.0f / DM) + RMS_EPS);
; }
; template <class Epi, bool ALIGN_EPI>
; __device__ __forceinline__ void gemm_phase(LAS unsigned char* lds, const Gemm g, int G, int cid, const Epi& E) {
;     ...
;     PG8_RTAB_FILL();
.LBB0_253:
	s_or_b64 exec, exec, s[28:29]
	v_readlane_b32 s0, v253, 13
	v_readlane_b32 s1, v253, 14
	s_mov_b32 s1, s31
	v_writelane_b32 v253, s0, 13
	v_mov_b32_e32 v187, v236
	s_nop 0
	v_writelane_b32 v253, s1, 14
	v_readlane_b32 s0, v254, 15
	v_readlane_b32 s1, v254, 16
	v_readlane_b32 s56, v253, 3
	v_readlane_b32 s58, v253, 5
	v_readlane_b32 s72, v253, 7
	s_andn2_b64 vcc, exec, s[0:1]
	v_readfirstlane_b32 s12, v187
	v_readlane_b32 s57, v253, 4
	v_readlane_b32 s59, v253, 6
	v_readlane_b32 s73, v253, 8
	s_cbranch_vccnz .LBB0_345
	s_movk_i32 s0, 0x100
	v_cmp_gt_i32_e64 s[38:39], s0, v187
	s_and_saveexec_b64 s[28:29], s[38:39]
	s_cbranch_execz .LBB0_256
	v_readlane_b32 s0, v255, 13
	s_nop 1
	v_add_u32_e32 v0, s0, v187
	v_ashrrev_i32_e32 v1, 31, v0
	v_lshlrev_b64 v[0:1], 7, v[0:1]
	v_lshl_add_u64 v[16:17], s[94:95], 0, v[0:1]
	global_load_dwordx4 v[0:3], v[16:17], off offset:48
	global_load_dwordx4 v[4:7], v[16:17], off offset:32
	global_load_dwordx4 v[8:11], v[16:17], off
	global_load_dwordx4 v[12:15], v[16:17], off offset:16
	global_load_dwordx4 v[22:25], v[16:17], off offset:112
	global_load_dwordx4 v[26:29], v[16:17], off offset:96
	global_load_dwordx4 v[30:33], v[16:17], off offset:80
	global_load_dwordx4 v[34:37], v[16:17], off offset:64
	s_waitcnt vmcnt(4)
	v_pk_add_f32 v[10:11], v[10:11], v[14:15]
	v_pk_add_f32 v[8:9], v[8:9], v[12:13]
	v_pk_add_f32 v[6:7], v[10:11], v[6:7]
	v_pk_add_f32 v[4:5], v[8:9], v[4:5]
	v_pk_add_f32 v[18:19], v[6:7], v[2:3]
	v_pk_add_f32 v[20:21], v[4:5], v[0:1]
	s_waitcnt vmcnt(0)
	v_pk_add_f32 v[14:15], v[18:19], v[36:37]
	v_pk_add_f32 v[12:13], v[20:21], v[34:35]
	v_pk_add_f32 v[10:11], v[14:15], v[32:33]
	v_pk_add_f32 v[8:9], v[12:13], v[30:31]
	v_pk_add_f32 v[6:7], v[10:11], v[28:29]
	v_pk_add_f32 v[4:5], v[8:9], v[26:27]
	v_pk_add_f32 v[2:3], v[6:7], v[24:25]
	v_pk_add_f32 v[0:1], v[4:5], v[22:23]
	s_nop 0
	v_pk_mov_b32 v[4:5], v[0:1], v[2:3] op_sel:[1,0]
	v_mov_b32_e32 v1, v3
	v_pk_add_f32 v[0:1], v[4:5], v[0:1]
	s_nop 0
	v_add_f32_e32 v0, v0, v1
	v_fmamk_f32 v0, v0, 0x3a000000, v237
	v_rsq_f32_e32 v0, v0
	v_lshl_add_u32 v1, v187, 2, 0
	v_add_u32_e32 v1, 0x20000, v1
	ds_write_b32 v1, v0

; __device__ __forceinline__ unsigned cvt_pk_bf16(float lo, float hi) { unsigned r; asm volatile("v_cvt_pk_bf16_f32 %0, %1, %2" : "=v"(r) : "v"(lo), "v"(hi)); return r; }
; template <class Epi, bool ALIGN_EPI>
; __device__ __forceinline__ void gemm_phase(LAS unsigned char* lds, const Gemm g, int G, int cid, const Epi& E) {
;     ...
;         if constexpr (Epi::ROWSCALE) { if (tid < 256) { f32x4 s_ = rl[0];
; #pragma unroll
;             for (int i = 1; i < NPART / 4; ++i) s_ += rl[i];
;             rtab[((ui + 1) & 1) * 256 + tid] = __builtin_amdgcn_rsqf(((s_.x + s_.y) + (s_.z + s_.w)) * (1.0f / DM) + RMS_EPS); } }
;     __device__ __forceinline__ void operator()(const f32x4 (&acc)[2][2][4][2], const Unit& u, int wr, int wc, int fr, int fq, const LAS float* rt) const {
;     ...
;                     const f32x4 v0 = acc[ai][bj][m][0] * sc * g0, v1 = acc[ai][bj][m][1] * sc * g1;
;                     u32x4 w; w.x = cvt_pk_bf16(v0[0], v0[1]); w.y = cvt_pk_bf16(v0[2], v0[3]); w.z = cvt_pk_bf16(v1[0], v1[1]); w.w = cvt_pk_bf16(v1[2], v1[3]);
;                     *(u32x4*)(QKV + ((size_t)(2 * u.pn + bj) * S + row) * HD + wc * 32 + 8 * fq) = w; } }
.LBB0_339:
	v_pk_mul_f32 v[4:5], v[4:5], v[16:17] op_sel_hi:[1,0]
	v_pk_mul_f32 v[2:3], v[2:3], v[16:17] op_sel_hi:[1,0]
	v_pk_mul_f32 v[4:5], v[164:165], v[4:5]
	v_pk_mul_f32 v[0:1], v[0:1], v[16:17] op_sel_hi:[1,0]
	v_pk_mul_f32 v[8:9], v[170:171], v[2:3]
	v_pk_mul_f32 v[2:3], v[168:169], v[0:1]
	v_cvt_pk_bf16_f32 v0, v4, v5
	v_lshl_add_u64 v[4:5], s[54:55], 0, v[18:19]
	v_lshl_add_u64 v[4:5], v[4:5], 0, s[30:31]
	v_pk_mul_f32 v[6:7], v[6:7], v[16:17] op_sel_hi:[1,0]
	v_lshl_add_u64 v[4:5], v[4:5], 0, v[138:139]
	s_and_b64 vcc, exec, s[42:43]
	s_mov_b64 s[42:43], -1
	v_pk_mul_f32 v[6:7], v[166:167], v[6:7]
	s_nop 0
	v_cvt_pk_bf16_f32 v1, v6, v7
	v_cvt_pk_bf16_f32 v2, v2, v3
	v_cvt_pk_bf16_f32 v3, v8, v9
	global_store_dwordx4 v[4:5], v[0:3], off
	s_cbranch_vccnz .LBB0_260
	s_and_saveexec_b64 s[42:43], s[38:39]
	s_cbranch_execz .LBB0_342
	s_waitcnt vmcnt(16)
	v_pk_add_f32 v[0:1], v[126:127], v[134:135]
	v_pk_add_f32 v[2:3], v[124:125], v[132:133]
	v_pk_add_f32 v[0:1], v[114:115], v[0:1]
	v_pk_add_f32 v[2:3], v[112:113], v[2:3]
	v_pk_add_f32 v[0:1], v[106:107], v[0:1]
	v_pk_add_f32 v[2:3], v[104:105], v[2:3]
	v_pk_add_f32 v[0:1], v[122:123], v[0:1]
	v_pk_add_f32 v[2:3], v[120:121], v[2:3]
	v_pk_add_f32 v[0:1], v[110:111], v[0:1]
	v_pk_add_f32 v[2:3], v[108:109], v[2:3]
	v_pk_add_f32 v[0:1], v[102:103], v[0:1]
	v_pk_add_f32 v[2:3], v[100:101], v[2:3]
	v_pk_add_f32 v[0:1], v[90:91], v[0:1]
	v_pk_add_f32 v[2:3], v[88:89], v[2:3]
	s_lshl_b32 s6, s86, 10
	v_pk_mov_b32 v[4:5], v[2:3], v[0:1] op_sel:[1,0]
	v_mov_b32_e32 v3, v1
	v_pk_add_f32 v[0:1], v[4:5], v[2:3]
	s_and_b32 s6, s6, 0x400
	v_add_f32_e32 v0, v0, v1
	v_fmamk_f32 v0, v0, 0x3a000000, v237
	v_rsq_f32_e32 v0, v0
	v_add_u32_e32 v1, s6, v191
	ds_write_b32 v1, v0

; #define PG8_RTAB_FILL() do { if constexpr (Epi::ROWSCALE) { if (tid < 256) rtab[(ui & 1) * 256 + tid] = row_rstd(E.part, cur.pm * 256 + tid); } } while (0)
; __device__ __forceinline__ float row_rstd(const float* part, int row) {
;     const f32x4* p = (const f32x4*)(part + (size_t)row * NPART); f32x4 s = p[0];
; #pragma unroll
;     for (int i = 1; i < NPART / 4; ++i) s += p[i];
;     const float t = (s.x + s.y) + (s.z + s.w);
;     return __builtin_amdgcn_rsqf(t * (1.0f / DM) + RMS_EPS);
; }
; template <class Epi, bool ALIGN_EPI>
; __device__ __forceinline__ void gemm_phase(LAS unsigned char* lds, const Gemm g, int G, int cid, const Epi& E) {
;     ...
;     PG8_RTAB_FILL();
.LBB0_800:
	v_readlane_b32 s0, v254, 57
	v_mov_b32_e32 v174, v236
	v_readlane_b32 s1, v254, 58
	s_mul_hi_u32 s72, s90, 0x2c00000
	s_mul_i32 s73, s90, 0x2c00000
	s_and_b64 vcc, exec, s[0:1]
	v_readfirstlane_b32 s28, v174
	s_cbranch_vccz .LBB0_826
	s_movk_i32 s0, 0x100
	v_cmp_gt_i32_e64 s[38:39], s0, v174
	s_and_saveexec_b64 s[22:23], s[38:39]
	s_cbranch_execz .LBB0_803
	v_readlane_b32 s0, v254, 60
	s_nop 1
	v_add_u32_e32 v0, s0, v174
	s_waitcnt lgkmcnt(0)
	v_ashrrev_i32_e32 v1, 31, v0
	v_lshlrev_b64 v[0:1], 7, v[0:1]
	v_lshl_add_u64 v[16:17], s[94:95], 0, v[0:1]
	global_load_dwordx4 v[0:3], v[16:17], off offset:48
	global_load_dwordx4 v[4:7], v[16:17], off offset:32
	global_load_dwordx4 v[8:11], v[16:17], off
	global_load_dwordx4 v[12:15], v[16:17], off offset:16
	global_load_dwordx4 v[22:25], v[16:17], off offset:112
	global_load_dwordx4 v[26:29], v[16:17], off offset:96
	global_load_dwordx4 v[30:33], v[16:17], off offset:80
	global_load_dwordx4 v[34:37], v[16:17], off offset:64
	s_waitcnt vmcnt(4)
	v_pk_add_f32 v[10:11], v[10:11], v[14:15]
	v_pk_add_f32 v[8:9], v[8:9], v[12:13]
	v_pk_add_f32 v[6:7], v[10:11], v[6:7]
	v_pk_add_f32 v[4:5], v[8:9], v[4:5]
	v_pk_add_f32 v[18:19], v[6:7], v[2:3]
	v_pk_add_f32 v[20:21], v[4:5], v[0:1]
	s_waitcnt vmcnt(0)
	v_pk_add_f32 v[14:15], v[18:19], v[36:37]
	v_pk_add_f32 v[12:13], v[20:21], v[34:35]
	v_pk_add_f32 v[10:11], v[14:15], v[32:33]
	v_pk_add_f32 v[8:9], v[12:13], v[30:31]
	v_pk_add_f32 v[6:7], v[10:11], v[28:29]
	v_pk_add_f32 v[4:5], v[8:9], v[26:27]
	v_pk_add_f32 v[2:3], v[6:7], v[24:25]
	v_pk_add_f32 v[0:1], v[4:5], v[22:23]
	s_nop 0
	v_pk_mov_b32 v[4:5], v[0:1], v[2:3] op_sel:[1,0]
	v_mov_b32_e32 v1, v3
	v_pk_add_f32 v[0:1], v[4:5], v[0:1]
	s_nop 0
	v_add_f32_e32 v0, v0, v1
	v_fmamk_f32 v0, v0, 0x3a000000, v237
	v_rsq_f32_e32 v0, v0
	v_lshl_add_u32 v1, v174, 2, 0
	v_add_u32_e32 v1, 0x20000, v1
	ds_write_b32 v1, v0

; template <class Epi, bool ALIGN_EPI>
; __device__ __forceinline__ void gemm_phase(LAS unsigned char* lds, const Gemm g, int G, int cid, const Epi& E) {
;     ...
; #pragma unroll
;         for (int a = 0; a < 2; ++a)
; #pragma unroll
;             for (int b = 0; b < 2; ++b)
; #pragma unroll
;                 for (int m = 0; m < 4; ++m)
; #pragma unroll
;                     for (int n = 0; n < 2; ++n) acc[a][b][m][n] = (f32x4){0.f, 0.f, 0.f, 0.f};
;         cur = nxt; cA = nA; cB = nB; ++ui;
.LBB0_812:
	s_and_b32 s6, s78, 0x7fffffff
	s_mov_b32 s7, s31
	s_lshl_b64 s[6:7], s[6:7], 14
	s_add_u32 s46, s0, s6
	s_addc_u32 s47, s1, s7
	s_and_b64 s[6:7], s[42:43], exec
	s_cselect_b32 s49, s47, s51
	s_cselect_b32 s48, s46, s50
	s_add_u32 s50, s50, 0x2c0000
	v_mov_b32_e32 v0, 0
	s_addc_u32 s51, s51, 0
	s_mov_b32 s91, -2
	v_mov_b32_e32 v1, v0
	v_mov_b32_e32 v2, v0
	v_mov_b32_e32 v3, v0
	v_mov_b32_e32 v4, v0
	v_mov_b32_e32 v5, v0
	v_mov_b32_e32 v6, v0
	v_mov_b32_e32 v7, v0
	v_mov_b32_e32 v16, v0
	v_mov_b32_e32 v17, v0
	v_mov_b32_e32 v18, v0
	v_mov_b32_e32 v19, v0
	v_mov_b32_e32 v20, v0
	v_mov_b32_e32 v21, v0
	v_mov_b32_e32 v22, v0
	v_mov_b32_e32 v23, v0
	v_mov_b32_e32 v32, v0
	v_mov_b32_e32 v33, v0
	v_mov_b32_e32 v34, v0
	v_mov_b32_e32 v35, v0
	v_mov_b32_e32 v36, v0
	v_mov_b32_e32 v37, v0
	v_mov_b32_e32 v38, v0
	v_mov_b32_e32 v39, v0
	v_mov_b32_e32 v48, v0
	v_mov_b32_e32 v49, v0
	v_mov_b32_e32 v50, v0
	v_mov_b32_e32 v51, v0
	v_mov_b32_e32 v52, v0
	v_mov_b32_e32 v53, v0
	v_mov_b32_e32 v54, v0
	v_mov_b32_e32 v55, v0
	v_mov_b32_e32 v8, v0
	v_mov_b32_e32 v9, v0
	v_mov_b32_e32 v10, v0
	v_mov_b32_e32 v11, v0
	v_mov_b32_e32 v12, v0
	v_mov_b32_e32 v13, v0
	v_mov_b32_e32 v14, v0
	v_mov_b32_e32 v15, v0
	v_mov_b32_e32 v24, v0
	v_mov_b32_e32 v25, v0
	v_mov_b32_e32 v26, v0
	v_mov_b32_e32 v27, v0
	v_mov_b32_e32 v28, v0
	v_mov_b32_e32 v29, v0
	v_mov_b32_e32 v30, v0
	v_mov_b32_e32 v31, v0
	v_mov_b32_e32 v40, v0
	v_mov_b32_e32 v41, v0
	v_mov_b32_e32 v42, v0
	v_mov_b32_e32 v43, v0
	v_mov_b32_e32 v44, v0
	v_mov_b32_e32 v45, v0
	v_mov_b32_e32 v46, v0
	v_mov_b32_e32 v47, v0
	v_mov_b32_e32 v56, v0
	v_mov_b32_e32 v57, v0
	v_mov_b32_e32 v58, v0
	v_mov_b32_e32 v59, v0
	v_mov_b32_e32 v60, v0
	v_mov_b32_e32 v61, v0
	v_mov_b32_e32 v62, v0
	v_mov_b32_e32 v63, v0
	v_mov_b32_e32 v64, v0
	v_mov_b32_e32 v65, v0
	v_mov_b32_e32 v66, v0
	v_mov_b32_e32 v67, v0
	v_mov_b32_e32 v68, v0
	v_mov_b32_e32 v69, v0
	v_mov_b32_e32 v70, v0
	v_mov_b32_e32 v71, v0
	v_mov_b32_e32 v80, v0
	v_mov_b32_e32 v81, v0
	v_mov_b32_e32 v82, v0
	v_mov_b32_e32 v83, v0
	v_mov_b32_e32 v84, v0
	v_mov_b32_e32 v85, v0
	v_mov_b32_e32 v86, v0
	v_mov_b32_e32 v87, v0
	v_mov_b32_e32 v96, v0
	v_mov_b32_e32 v97, v0
	v_mov_b32_e32 v98, v0
	v_mov_b32_e32 v99, v0
	v_mov_b32_e32 v100, v0
	v_mov_b32_e32 v101, v0
	v_mov_b32_e32 v102, v0
	v_mov_b32_e32 v103, v0
	v_mov_b32_e32 v112, v0
	v_mov_b32_e32 v113, v0
	v_mov_b32_e32 v114, v0
	v_mov_b32_e32 v115, v0
	v_mov_b32_e32 v116, v0
	v_mov_b32_e32 v117, v0
	v_mov_b32_e32 v118, v0
	v_mov_b32_e32 v119, v0
	v_mov_b32_e32 v72, v0
	v_mov_b32_e32 v73, v0
	v_mov_b32_e32 v74, v0
	v_mov_b32_e32 v75, v0
	v_mov_b32_e32 v76, v0
	v_mov_b32_e32 v77, v0
	v_mov_b32_e32 v78, v0
	v_mov_b32_e32 v79, v0
	v_mov_b32_e32 v88, v0
	v_mov_b32_e32 v89, v0
	v_mov_b32_e32 v90, v0
	v_mov_b32_e32 v91, v0
	v_mov_b32_e32 v92, v0
	v_mov_b32_e32 v93, v0
	v_mov_b32_e32 v94, v0
	v_mov_b32_e32 v95, v0
	v_mov_b32_e32 v104, v0
	v_mov_b32_e32 v105, v0
	v_mov_b32_e32 v106, v0
	v_mov_b32_e32 v107, v0
	v_mov_b32_e32 v108, v0
	v_mov_b32_e32 v109, v0
	v_mov_b32_e32 v110, v0
	v_mov_b32_e32 v111, v0
	v_mov_b32_e32 v120, v0
	v_mov_b32_e32 v121, v0
	v_mov_b32_e32 v122, v0
	v_mov_b32_e32 v123, v0
	v_mov_b32_e32 v124, v0
	v_mov_b32_e32 v125, v0
	v_mov_b32_e32 v126, v0
	v_mov_b32_e32 v127, v0
	s_branch .LBB0_814

; __device__ __forceinline__ unsigned cvtpk_s(float lo, float hi) { f32x2_t v = {lo, hi}; bf16x2_t b = __builtin_convertvector(v, bf16x2_t); return __builtin_bit_cast(unsigned, b); }
;     __device__ __forceinline__ void operator()(const f32x4 (&acc)[2][2][4][2], const Unit& u, int wr, int wc, int fr, int fq, const LAS float* rt) const {
;         const int row0 = u.pm * BM + wr * 64 + fr;
; #pragma unroll
;         for (int ai = 0; ai < 2; ++ai)
; #pragma unroll
;             for (int m = 0; m < 4; ++m) { const int row = row0 + ai * HALF + m * 16; const float rs = rt[ai * HALF + wr * 64 + m * 16 + fr];
;                 const f32x4 g0 = acc[ai][0][m][0] * rs, g1 = acc[ai][0][m][1] * rs, u0 = acc[ai][1][m][0] * rs, u1 = acc[ai][1][m][1] * rs;
;                 f32x4 e0 = g0 * (-LOG2E), e1 = g1 * (-LOG2E);
; #pragma unroll
;                 for (int i = 0; i < 4; ++i) { e0[i] = __builtin_amdgcn_exp2f(e0[i]); e1[i] = __builtin_amdgcn_exp2f(e1[i]); }
;                 e0 += 1.0f; e1 += 1.0f;
; #pragma unroll
;                 for (int i = 0; i < 4; ++i) { e0[i] = __builtin_amdgcn_rcpf(e0[i]); e1[i] = __builtin_amdgcn_rcpf(e1[i]); }
;                 const f32x4 o0 = g0 * e0 * u0, o1 = g1 * e1 * u1;
;                 u32x4 w; w.x = cvtpk_s(o0[0], o0[1]); w.y = cvtpk_s(o0[2], o0[3]); w.z = cvtpk_s(o1[0], o1[1]); w.w = cvtpk_s(o1[2], o1[3]);
;                 *(u32x4*)(H + (size_t)row * FF + u.pn * HALF + wc * 32 + 8 * fq) = w; }
.LBB0_820:
	s_or_b64 exec, exec, s[42:43]
	s_lshl_b32 s6, s90, 10
	s_and_b32 s6, s6, 0x400
	v_add_u32_e32 v181, s6, v177
	ds_read2_b32 v[182:183], v181 offset1:16
	v_lshl_add_u32 v180, s87, 8, v175
	s_lshl_b32 s6, s86, 7
	s_ashr_i32 s7, s6, 31
	s_and_b64 vcc, exec, s[40:41]
	s_waitcnt lgkmcnt(0)
	v_pk_mul_f32 v[124:125], v[124:125], v[182:183] op_sel_hi:[1,0]
	v_pk_mul_f32 v[120:121], v[120:121], v[182:183] op_sel_hi:[1,0]
	v_pk_mul_f32 v[126:127], v[126:127], v[182:183] op_sel_hi:[1,0]
	v_pk_mul_f32 v[122:123], v[122:123], v[182:183] op_sel_hi:[1,0]
	v_pk_mul_f32 v[186:187], v[124:125], s[10:11] op_sel_hi:[1,0]
	v_pk_mul_f32 v[190:191], v[120:121], s[10:11] op_sel_hi:[1,0]
	v_pk_mul_f32 v[184:185], v[126:127], s[10:11] op_sel_hi:[1,0]
	v_pk_mul_f32 v[188:189], v[122:123], s[10:11] op_sel_hi:[1,0]
	v_exp_f32_e32 v186, v186
	v_exp_f32_e32 v190, v190
	v_exp_f32_e32 v187, v187
	v_exp_f32_e32 v191, v191
	v_exp_f32_e32 v184, v184
	v_exp_f32_e32 v188, v188
	v_exp_f32_e32 v185, v185
	v_exp_f32_e32 v189, v189
	v_pk_add_f32 v[186:187], v[186:187], 1.0 op_sel_hi:[1,0]
	v_pk_add_f32 v[190:191], v[190:191], 1.0 op_sel_hi:[1,0]
	v_pk_add_f32 v[184:185], v[184:185], 1.0 op_sel_hi:[1,0]
	v_pk_add_f32 v[188:189], v[188:189], 1.0 op_sel_hi:[1,0]
	v_rcp_f32_e32 v186, v186
	v_rcp_f32_e32 v190, v190
	v_rcp_f32_e32 v187, v187
	v_rcp_f32_e32 v191, v191
	v_rcp_f32_e32 v184, v184
	v_rcp_f32_e32 v188, v188
	v_rcp_f32_e32 v185, v185
	v_rcp_f32_e32 v189, v189
	v_pk_mul_f32 v[116:117], v[116:117], v[182:183] op_sel_hi:[1,0]
	v_pk_mul_f32 v[112:113], v[112:113], v[182:183] op_sel_hi:[1,0]
	v_pk_mul_f32 v[124:125], v[124:125], v[186:187]
	v_pk_mul_f32 v[120:121], v[120:121], v[190:191]
	v_pk_mul_f32 v[118:119], v[118:119], v[182:183] op_sel_hi:[1,0]
	v_pk_mul_f32 v[114:115], v[114:115], v[182:183] op_sel_hi:[1,0]
	v_pk_mul_f32 v[126:127], v[126:127], v[184:185]
	v_pk_mul_f32 v[116:117], v[116:117], v[124:125]
	v_pk_mul_f32 v[122:123], v[122:123], v[188:189]
	v_pk_mul_f32 v[112:113], v[112:113], v[120:121]
	v_pk_mul_f32 v[118:119], v[118:119], v[126:127]
	v_pk_mul_f32 v[122:123], v[114:115], v[122:123]
	v_cvt_pk_bf16_f32 v114, v116, v117
	v_cvt_pk_bf16_f32 v116, v112, v113
	v_mov_b64_e32 v[112:113], s[8:9]
	v_cvt_pk_bf16_f32 v115, v118, v119
	v_mad_i64_i32 v[118:119], s[42:43], v180, s97, v[112:113]
	s_lshl_b64 s[42:43], s[6:7], 1
	s_nop 0
	v_lshl_add_u64 v[118:119], v[118:119], 0, s[42:43]
	v_lshl_add_u64 v[118:119], v[118:119], 0, s[30:31]
	v_cvt_pk_bf16_f32 v117, v122, v123
	v_lshl_add_u64 v[118:119], v[118:119], 0, v[138:139]
	global_store_dwordx4 v[118:119], v[114:117], off
	s_mov_b64 s[40:41], -1
	s_nop 0
	v_mov_b32_e32 v114, v183
	v_pk_mul_f32 v[110:111], v[110:111], v[114:115] op_sel_hi:[1,0]
	v_pk_mul_f32 v[106:107], v[106:107], v[114:115] op_sel_hi:[1,0]
	v_pk_mul_f32 v[104:105], v[104:105], v[114:115] op_sel_hi:[1,0]
	v_pk_mul_f32 v[116:117], v[110:111], s[10:11] op_sel_hi:[1,0]
	v_pk_mul_f32 v[108:109], v[108:109], v[114:115] op_sel_hi:[1,0]
	v_pk_mul_f32 v[120:121], v[106:107], s[10:11] op_sel_hi:[1,0]
	v_pk_mul_f32 v[122:123], v[104:105], s[10:11] op_sel_hi:[1,0]
	v_exp_f32_e32 v116, v116
	v_exp_f32_e32 v117, v117
	v_pk_mul_f32 v[118:119], v[108:109], s[10:11] op_sel_hi:[1,0]
	v_exp_f32_e32 v122, v122
	v_exp_f32_e32 v123, v123
	v_exp_f32_e32 v120, v120
	v_exp_f32_e32 v121, v121
	v_exp_f32_e32 v118, v118
	v_exp_f32_e32 v119, v119
	v_pk_add_f32 v[116:117], v[116:117], 1.0 op_sel_hi:[1,0]
	v_pk_add_f32 v[120:121], v[120:121], 1.0 op_sel_hi:[1,0]
	v_pk_add_f32 v[122:123], v[122:123], 1.0 op_sel_hi:[1,0]
	v_rcp_f32_e32 v116, v116
	v_rcp_f32_e32 v117, v117
	v_pk_add_f32 v[118:119], v[118:119], 1.0 op_sel_hi:[1,0]
	v_rcp_f32_e32 v122, v122
	v_rcp_f32_e32 v123, v123
	v_rcp_f32_e32 v120, v120
	v_rcp_f32_e32 v121, v121
	v_rcp_f32_e32 v118, v118
	v_rcp_f32_e32 v119, v119
	v_pk_mul_f32 v[102:103], v[102:103], v[114:115] op_sel_hi:[1,0]
	v_pk_mul_f32 v[100:101], v[100:101], v[114:115] op_sel_hi:[1,0]
	v_or_b32_e32 v115, 16, v180
	v_pk_mul_f32 v[110:111], v[110:111], v[116:117]
	v_pk_mul_f32 v[98:99], v[98:99], v[114:115] op_sel_hi:[1,0]
	v_pk_mul_f32 v[96:97], v[96:97], v[114:115] op_sel_hi:[1,0]
	v_pk_mul_f32 v[102:103], v[102:103], v[110:111]
	v_pk_mul_f32 v[104:105], v[104:105], v[122:123]
	v_pk_mul_f32 v[106:107], v[106:107], v[120:121]
	v_pk_mul_f32 v[108:109], v[108:109], v[118:119]
	v_pk_mul_f32 v[106:107], v[98:99], v[106:107]
	v_pk_mul_f32 v[98:99], v[96:97], v[104:105]
	v_cvt_pk_bf16_f32 v97, v102, v103
	ds_read2_b32 v[102:103], v181 offset0:32 offset1:48
	v_pk_mul_f32 v[100:101], v[100:101], v[108:109]
	v_cvt_pk_bf16_f32 v98, v98, v99
	v_cvt_pk_bf16_f32 v96, v100, v101
	v_mad_i64_i32 v[100:101], s[6:7], v115, s97, v[112:113]
	v_lshl_add_u64 v[100:101], v[100:101], 0, s[42:43]
	v_lshl_add_u64 v[100:101], v[100:101], 0, s[30:31]
	v_cvt_pk_bf16_f32 v99, v106, v107
	v_lshl_add_u64 v[100:101], v[100:101], 0, v[138:139]
	s_waitcnt lgkmcnt(0)
; __device__ __forceinline__ unsigned cvtpk_s(float lo, float hi) { f32x2_t v = {lo, hi}; bf16x2_t b = __builtin_convertvector(v, bf16x2_t); return __builtin_bit_cast(unsigned, b); }
;     __device__ __forceinline__ void operator()(const f32x4 (&acc)[2][2][4][2], const Unit& u, int wr, int wc, int fr, int fq, const LAS float* rt) const {
;         const int row0 = u.pm * BM + wr * 64 + fr;
; #pragma unroll
;         for (int ai = 0; ai < 2; ++ai)
; #pragma unroll
;             for (int m = 0; m < 4; ++m) { const int row = row0 + ai * HALF + m * 16; const float rs = rt[ai * HALF + wr * 64 + m * 16 + fr];
;                 const f32x4 g0 = acc[ai][0][m][0] * rs, g1 = acc[ai][0][m][1] * rs, u0 = acc[ai][1][m][0] * rs, u1 = acc[ai][1][m][1] * rs;
;                 f32x4 e0 = g0 * (-LOG2E), e1 = g1 * (-LOG2E);
; #pragma unroll
;                 for (int i = 0; i < 4; ++i) { e0[i] = __builtin_amdgcn_exp2f(e0[i]); e1[i] = __builtin_amdgcn_exp2f(e1[i]); }
;                 e0 += 1.0f; e1 += 1.0f;
; #pragma unroll
;                 for (int i = 0; i < 4; ++i) { e0[i] = __builtin_amdgcn_rcpf(e0[i]); e1[i] = __builtin_amdgcn_rcpf(e1[i]); }
;                 const f32x4 o0 = g0 * e0 * u0, o1 = g1 * e1 * u1;
;                 u32x4 w; w.x = cvtpk_s(o0[0], o0[1]); w.y = cvtpk_s(o0[2], o0[3]); w.z = cvtpk_s(o1[0], o1[1]); w.w = cvtpk_s(o1[2], o1[3]);
;                 *(u32x4*)(H + (size_t)row * FF + u.pn * HALF + wc * 32 + 8 * fq) = w; }
	v_pk_mul_f32 v[92:93], v[92:93], v[102:103] op_sel_hi:[1,0]
	global_store_dwordx4 v[100:101], v[96:99], off
	v_pk_mul_f32 v[90:91], v[90:91], v[102:103] op_sel_hi:[1,0]
	v_pk_mul_f32 v[88:89], v[88:89], v[102:103] op_sel_hi:[1,0]
	v_pk_mul_f32 v[98:99], v[92:93], s[10:11] op_sel_hi:[1,0]
	v_pk_mul_f32 v[100:101], v[90:91], s[10:11] op_sel_hi:[1,0]
	v_pk_mul_f32 v[104:105], v[88:89], s[10:11] op_sel_hi:[1,0]
	v_exp_f32_e32 v98, v98
	v_exp_f32_e32 v99, v99
	v_pk_mul_f32 v[94:95], v[94:95], v[102:103] op_sel_hi:[1,0]
	v_exp_f32_e32 v104, v104
	v_exp_f32_e32 v105, v105
	v_exp_f32_e32 v100, v100
	v_exp_f32_e32 v101, v101
	v_pk_mul_f32 v[96:97], v[94:95], s[10:11] op_sel_hi:[1,0]
	v_pk_add_f32 v[98:99], v[98:99], 1.0 op_sel_hi:[1,0]
	v_exp_f32_e32 v96, v96
	v_exp_f32_e32 v97, v97
	v_pk_add_f32 v[100:101], v[100:101], 1.0 op_sel_hi:[1,0]
	v_pk_add_f32 v[104:105], v[104:105], 1.0 op_sel_hi:[1,0]
	v_rcp_f32_e32 v98, v98
	v_rcp_f32_e32 v99, v99
	v_rcp_f32_e32 v104, v104
	v_rcp_f32_e32 v105, v105
	v_rcp_f32_e32 v100, v100
	v_rcp_f32_e32 v101, v101
	v_pk_add_f32 v[96:97], v[96:97], 1.0 op_sel_hi:[1,0]
	v_pk_mul_f32 v[84:85], v[84:85], v[102:103] op_sel_hi:[1,0]
	v_rcp_f32_e32 v96, v96
	v_rcp_f32_e32 v97, v97
	v_pk_mul_f32 v[92:93], v[92:93], v[98:99]
	v_or_b32_e32 v106, 32, v180
	v_pk_mul_f32 v[82:83], v[82:83], v[102:103] op_sel_hi:[1,0]
	v_pk_mul_f32 v[80:81], v[80:81], v[102:103] op_sel_hi:[1,0]
	v_pk_mul_f32 v[84:85], v[84:85], v[92:93]
	v_pk_mul_f32 v[88:89], v[88:89], v[104:105]
	v_pk_mul_f32 v[90:91], v[90:91], v[100:101]
	v_pk_mul_f32 v[86:87], v[86:87], v[102:103] op_sel_hi:[1,0]
	v_pk_mul_f32 v[90:91], v[82:83], v[90:91]
	v_pk_mul_f32 v[82:83], v[80:81], v[88:89]
	v_cvt_pk_bf16_f32 v80, v84, v85
	v_mad_i64_i32 v[84:85], s[6:7], v106, s97, v[112:113]
	v_pk_mul_f32 v[94:95], v[94:95], v[96:97]
	v_lshl_add_u64 v[84:85], v[84:85], 0, s[42:43]
	v_pk_mul_f32 v[86:87], v[86:87], v[94:95]
	v_lshl_add_u64 v[84:85], v[84:85], 0, s[30:31]
	v_cvt_pk_bf16_f32 v81, v86, v87
	v_cvt_pk_bf16_f32 v82, v82, v83
	v_cvt_pk_bf16_f32 v83, v90, v91
	v_lshl_add_u64 v[84:85], v[84:85], 0, v[138:139]
	global_store_dwordx4 v[84:85], v[80:83], off
	s_nop 1
	v_mov_b32_e32 v80, v103
	v_pk_mul_f32 v[78:79], v[78:79], v[80:81] op_sel_hi:[1,0]
	v_pk_mul_f32 v[74:75], v[74:75], v[80:81] op_sel_hi:[1,0]
	v_pk_mul_f32 v[72:73], v[72:73], v[80:81] op_sel_hi:[1,0]
	v_pk_mul_f32 v[82:83], v[78:79], s[10:11] op_sel_hi:[1,0]
	v_pk_mul_f32 v[76:77], v[76:77], v[80:81] op_sel_hi:[1,0]
	v_pk_mul_f32 v[86:87], v[74:75], s[10:11] op_sel_hi:[1,0]
	v_pk_mul_f32 v[88:89], v[72:73], s[10:11] op_sel_hi:[1,0]
	v_exp_f32_e32 v82, v82
	v_exp_f32_e32 v83, v83
	v_pk_mul_f32 v[84:85], v[76:77], s[10:11] op_sel_hi:[1,0]
	v_exp_f32_e32 v88, v88
	v_exp_f32_e32 v89, v89
	v_exp_f32_e32 v86, v86
	v_exp_f32_e32 v87, v87
	v_exp_f32_e32 v84, v84
	v_exp_f32_e32 v85, v85
	v_pk_add_f32 v[82:83], v[82:83], 1.0 op_sel_hi:[1,0]
	v_pk_add_f32 v[86:87], v[86:87], 1.0 op_sel_hi:[1,0]
	v_pk_add_f32 v[88:89], v[88:89], 1.0 op_sel_hi:[1,0]
	v_rcp_f32_e32 v82, v82
	v_rcp_f32_e32 v83, v83
	v_pk_add_f32 v[84:85], v[84:85], 1.0 op_sel_hi:[1,0]
	v_rcp_f32_e32 v88, v88
	v_rcp_f32_e32 v89, v89
	v_rcp_f32_e32 v86, v86
	v_rcp_f32_e32 v87, v87
	v_rcp_f32_e32 v84, v84
	v_rcp_f32_e32 v85, v85
	v_pk_mul_f32 v[70:71], v[70:71], v[80:81] op_sel_hi:[1,0]
	v_pk_mul_f32 v[68:69], v[68:69], v[80:81] op_sel_hi:[1,0]
	v_or_b32_e32 v81, 48, v180
	v_pk_mul_f32 v[78:79], v[78:79], v[82:83]
	v_pk_mul_f32 v[66:67], v[66:67], v[80:81] op_sel_hi:[1,0]
	v_pk_mul_f32 v[64:65], v[64:65], v[80:81] op_sel_hi:[1,0]
	v_pk_mul_f32 v[70:71], v[70:71], v[78:79]
	v_pk_mul_f32 v[72:73], v[72:73], v[88:89]
	v_pk_mul_f32 v[74:75], v[74:75], v[86:87]
	v_pk_mul_f32 v[76:77], v[76:77], v[84:85]
	v_pk_mul_f32 v[74:75], v[66:67], v[74:75]
	v_pk_mul_f32 v[66:67], v[64:65], v[72:73]
	v_cvt_pk_bf16_f32 v65, v70, v71
	ds_read2_b32 v[70:71], v181 offset0:128 offset1:144
	v_pk_mul_f32 v[68:69], v[68:69], v[76:77]
	v_cvt_pk_bf16_f32 v66, v66, v67
	v_cvt_pk_bf16_f32 v64, v68, v69
	v_mad_i64_i32 v[68:69], s[6:7], v81, s97, v[112:113]
	v_lshl_add_u64 v[68:69], v[68:69], 0, s[42:43]
	v_lshl_add_u64 v[68:69], v[68:69], 0, s[30:31]
	v_cvt_pk_bf16_f32 v67, v74, v75
	v_lshl_add_u64 v[68:69], v[68:69], 0, v[138:139]
	s_waitcnt lgkmcnt(0)
; __device__ __forceinline__ unsigned cvtpk_s(float lo, float hi) { f32x2_t v = {lo, hi}; bf16x2_t b = __builtin_convertvector(v, bf16x2_t); return __builtin_bit_cast(unsigned, b); }
;     __device__ __forceinline__ void operator()(const f32x4 (&acc)[2][2][4][2], const Unit& u, int wr, int wc, int fr, int fq, const LAS float* rt) const {
;         const int row0 = u.pm * BM + wr * 64 + fr;
; #pragma unroll
;         for (int ai = 0; ai < 2; ++ai)
; #pragma unroll
;             for (int m = 0; m < 4; ++m) { const int row = row0 + ai * HALF + m * 16; const float rs = rt[ai * HALF + wr * 64 + m * 16 + fr];
;                 const f32x4 g0 = acc[ai][0][m][0] * rs, g1 = acc[ai][0][m][1] * rs, u0 = acc[ai][1][m][0] * rs, u1 = acc[ai][1][m][1] * rs;
;                 f32x4 e0 = g0 * (-LOG2E), e1 = g1 * (-LOG2E);
; #pragma unroll
;                 for (int i = 0; i < 4; ++i) { e0[i] = __builtin_amdgcn_exp2f(e0[i]); e1[i] = __builtin_amdgcn_exp2f(e1[i]); }
;                 e0 += 1.0f; e1 += 1.0f;
; #pragma unroll
;                 for (int i = 0; i < 4; ++i) { e0[i] = __builtin_amdgcn_rcpf(e0[i]); e1[i] = __builtin_amdgcn_rcpf(e1[i]); }
;                 const f32x4 o0 = g0 * e0 * u0, o1 = g1 * e1 * u1;
;                 u32x4 w; w.x = cvtpk_s(o0[0], o0[1]); w.y = cvtpk_s(o0[2], o0[3]); w.z = cvtpk_s(o1[0], o1[1]); w.w = cvtpk_s(o1[2], o1[3]);
;                 *(u32x4*)(H + (size_t)row * FF + u.pn * HALF + wc * 32 + 8 * fq) = w; }
	v_pk_mul_f32 v[60:61], v[60:61], v[70:71] op_sel_hi:[1,0]
	global_store_dwordx4 v[68:69], v[64:67], off
	v_pk_mul_f32 v[58:59], v[58:59], v[70:71] op_sel_hi:[1,0]
	v_pk_mul_f32 v[56:57], v[56:57], v[70:71] op_sel_hi:[1,0]
	v_pk_mul_f32 v[66:67], v[60:61], s[10:11] op_sel_hi:[1,0]
	v_pk_mul_f32 v[68:69], v[58:59], s[10:11] op_sel_hi:[1,0]
	v_pk_mul_f32 v[72:73], v[56:57], s[10:11] op_sel_hi:[1,0]
	v_exp_f32_e32 v66, v66
	v_exp_f32_e32 v67, v67
	v_pk_mul_f32 v[62:63], v[62:63], v[70:71] op_sel_hi:[1,0]
	v_exp_f32_e32 v72, v72
	v_exp_f32_e32 v73, v73
	v_exp_f32_e32 v68, v68
	v_exp_f32_e32 v69, v69
	v_pk_mul_f32 v[64:65], v[62:63], s[10:11] op_sel_hi:[1,0]
	v_pk_add_f32 v[66:67], v[66:67], 1.0 op_sel_hi:[1,0]
	v_exp_f32_e32 v64, v64
	v_exp_f32_e32 v65, v65
	v_pk_add_f32 v[68:69], v[68:69], 1.0 op_sel_hi:[1,0]
	v_pk_add_f32 v[72:73], v[72:73], 1.0 op_sel_hi:[1,0]
	v_rcp_f32_e32 v66, v66
	v_rcp_f32_e32 v67, v67
	v_rcp_f32_e32 v72, v72
	v_rcp_f32_e32 v73, v73
	v_rcp_f32_e32 v68, v68
	v_rcp_f32_e32 v69, v69
	v_pk_add_f32 v[64:65], v[64:65], 1.0 op_sel_hi:[1,0]
	v_pk_mul_f32 v[52:53], v[52:53], v[70:71] op_sel_hi:[1,0]
	v_rcp_f32_e32 v64, v64
	v_rcp_f32_e32 v65, v65
	v_pk_mul_f32 v[60:61], v[60:61], v[66:67]
	v_add_u32_e32 v74, 0x80, v180
	v_pk_mul_f32 v[50:51], v[50:51], v[70:71] op_sel_hi:[1,0]
	v_pk_mul_f32 v[48:49], v[48:49], v[70:71] op_sel_hi:[1,0]
	v_pk_mul_f32 v[52:53], v[52:53], v[60:61]
	v_pk_mul_f32 v[56:57], v[56:57], v[72:73]
	v_pk_mul_f32 v[58:59], v[58:59], v[68:69]
	v_pk_mul_f32 v[54:55], v[54:55], v[70:71] op_sel_hi:[1,0]
	v_pk_mul_f32 v[58:59], v[50:51], v[58:59]
	v_pk_mul_f32 v[50:51], v[48:49], v[56:57]
	v_cvt_pk_bf16_f32 v48, v52, v53
	v_mad_i64_i32 v[52:53], s[6:7], v74, s97, v[112:113]
	v_pk_mul_f32 v[62:63], v[62:63], v[64:65]
	v_lshl_add_u64 v[52:53], v[52:53], 0, s[42:43]
	v_pk_mul_f32 v[54:55], v[54:55], v[62:63]
	v_lshl_add_u64 v[52:53], v[52:53], 0, s[30:31]
	v_cvt_pk_bf16_f32 v49, v54, v55
	v_cvt_pk_bf16_f32 v50, v50, v51
	v_cvt_pk_bf16_f32 v51, v58, v59
	v_lshl_add_u64 v[52:53], v[52:53], 0, v[138:139]
	global_store_dwordx4 v[52:53], v[48:51], off
	s_nop 1
	v_mov_b32_e32 v48, v71
	v_pk_mul_f32 v[46:47], v[46:47], v[48:49] op_sel_hi:[1,0]
	v_pk_mul_f32 v[42:43], v[42:43], v[48:49] op_sel_hi:[1,0]
	v_pk_mul_f32 v[40:41], v[40:41], v[48:49] op_sel_hi:[1,0]
	v_pk_mul_f32 v[50:51], v[46:47], s[10:11] op_sel_hi:[1,0]
	v_pk_mul_f32 v[44:45], v[44:45], v[48:49] op_sel_hi:[1,0]
	v_pk_mul_f32 v[54:55], v[42:43], s[10:11] op_sel_hi:[1,0]
	v_pk_mul_f32 v[56:57], v[40:41], s[10:11] op_sel_hi:[1,0]
	v_exp_f32_e32 v50, v50
	v_exp_f32_e32 v51, v51
	v_pk_mul_f32 v[52:53], v[44:45], s[10:11] op_sel_hi:[1,0]
	v_exp_f32_e32 v56, v56
	v_exp_f32_e32 v57, v57
	v_exp_f32_e32 v54, v54
	v_exp_f32_e32 v55, v55
	v_exp_f32_e32 v52, v52
	v_exp_f32_e32 v53, v53
	v_pk_add_f32 v[50:51], v[50:51], 1.0 op_sel_hi:[1,0]
	v_pk_add_f32 v[54:55], v[54:55], 1.0 op_sel_hi:[1,0]
	v_pk_add_f32 v[56:57], v[56:57], 1.0 op_sel_hi:[1,0]
	v_rcp_f32_e32 v50, v50
	v_rcp_f32_e32 v51, v51
	v_pk_add_f32 v[52:53], v[52:53], 1.0 op_sel_hi:[1,0]
	v_rcp_f32_e32 v56, v56
	v_rcp_f32_e32 v57, v57
	v_rcp_f32_e32 v54, v54
	v_rcp_f32_e32 v55, v55
	v_rcp_f32_e32 v52, v52
	v_rcp_f32_e32 v53, v53
	v_pk_mul_f32 v[38:39], v[38:39], v[48:49] op_sel_hi:[1,0]
	v_pk_mul_f32 v[36:37], v[36:37], v[48:49] op_sel_hi:[1,0]
	v_add_u32_e32 v49, 0x90, v180
	v_pk_mul_f32 v[46:47], v[46:47], v[50:51]
	v_pk_mul_f32 v[34:35], v[34:35], v[48:49] op_sel_hi:[1,0]
	v_pk_mul_f32 v[32:33], v[32:33], v[48:49] op_sel_hi:[1,0]
	v_pk_mul_f32 v[38:39], v[38:39], v[46:47]
	v_pk_mul_f32 v[40:41], v[40:41], v[56:57]
	v_pk_mul_f32 v[42:43], v[42:43], v[54:55]
	v_pk_mul_f32 v[44:45], v[44:45], v[52:53]
	v_pk_mul_f32 v[42:43], v[34:35], v[42:43]
	v_pk_mul_f32 v[34:35], v[32:33], v[40:41]
	v_cvt_pk_bf16_f32 v33, v38, v39
	ds_read2_b32 v[38:39], v181 offset0:160 offset1:176
	v_pk_mul_f32 v[36:37], v[36:37], v[44:45]
	v_cvt_pk_bf16_f32 v34, v34, v35
	v_cvt_pk_bf16_f32 v32, v36, v37
	v_mad_i64_i32 v[36:37], s[6:7], v49, s97, v[112:113]
	v_lshl_add_u64 v[36:37], v[36:37], 0, s[42:43]
	v_lshl_add_u64 v[36:37], v[36:37], 0, s[30:31]
	v_cvt_pk_bf16_f32 v35, v42, v43
	v_lshl_add_u64 v[36:37], v[36:37], 0, v[138:139]
	s_waitcnt lgkmcnt(0)
; __device__ __forceinline__ unsigned cvtpk_s(float lo, float hi) { f32x2_t v = {lo, hi}; bf16x2_t b = __builtin_convertvector(v, bf16x2_t); return __builtin_bit_cast(unsigned, b); }
; template <class Epi, bool ALIGN_EPI>
; __device__ __forceinline__ void gemm_phase(LAS unsigned char* lds, const Gemm g, int G, int cid, const Epi& E) {
;     ...
;         if constexpr (Epi::ROWSCALE) { if (tid < 256) { f32x4 s_ = rl[0];
; #pragma unroll
;             for (int i = 1; i < NPART / 4; ++i) s_ += rl[i];
;             rtab[((ui + 1) & 1) * 256 + tid] = __builtin_amdgcn_rsqf(((s_.x + s_.y) + (s_.z + s_.w)) * (1.0f / DM) + RMS_EPS); } }
;     __device__ __forceinline__ void operator()(const f32x4 (&acc)[2][2][4][2], const Unit& u, int wr, int wc, int fr, int fq, const LAS float* rt) const {
;     ...
;             for (int m = 0; m < 4; ++m) { const int row = row0 + ai * HALF + m * 16; const float rs = rt[ai * HALF + wr * 64 + m * 16 + fr];
;                 const f32x4 g0 = acc[ai][0][m][0] * rs, g1 = acc[ai][0][m][1] * rs, u0 = acc[ai][1][m][0] * rs, u1 = acc[ai][1][m][1] * rs;
;                 f32x4 e0 = g0 * (-LOG2E), e1 = g1 * (-LOG2E);
; #pragma unroll
;                 for (int i = 0; i < 4; ++i) { e0[i] = __builtin_amdgcn_exp2f(e0[i]); e1[i] = __builtin_amdgcn_exp2f(e1[i]); }
;                 e0 += 1.0f; e1 += 1.0f;
; #pragma unroll
;                 for (int i = 0; i < 4; ++i) { e0[i] = __builtin_amdgcn_rcpf(e0[i]); e1[i] = __builtin_amdgcn_rcpf(e1[i]); }
;                 const f32x4 o0 = g0 * e0 * u0, o1 = g1 * e1 * u1;
;                 u32x4 w; w.x = cvtpk_s(o0[0], o0[1]); w.y = cvtpk_s(o0[2], o0[3]); w.z = cvtpk_s(o1[0], o1[1]); w.w = cvtpk_s(o1[2], o1[3]);
;                 *(u32x4*)(H + (size_t)row * FF + u.pn * HALF + wc * 32 + 8 * fq) = w; }
	v_pk_mul_f32 v[28:29], v[28:29], v[38:39] op_sel_hi:[1,0]
	global_store_dwordx4 v[36:37], v[32:35], off
	v_pk_mul_f32 v[26:27], v[26:27], v[38:39] op_sel_hi:[1,0]
	v_pk_mul_f32 v[24:25], v[24:25], v[38:39] op_sel_hi:[1,0]
	v_pk_mul_f32 v[34:35], v[28:29], s[10:11] op_sel_hi:[1,0]
	v_pk_mul_f32 v[36:37], v[26:27], s[10:11] op_sel_hi:[1,0]
	v_pk_mul_f32 v[40:41], v[24:25], s[10:11] op_sel_hi:[1,0]
	v_exp_f32_e32 v34, v34
	v_exp_f32_e32 v35, v35
	v_pk_mul_f32 v[30:31], v[30:31], v[38:39] op_sel_hi:[1,0]
	v_exp_f32_e32 v40, v40
	v_exp_f32_e32 v41, v41
	v_exp_f32_e32 v36, v36
	v_exp_f32_e32 v37, v37
	v_pk_mul_f32 v[32:33], v[30:31], s[10:11] op_sel_hi:[1,0]
	v_pk_add_f32 v[34:35], v[34:35], 1.0 op_sel_hi:[1,0]
	v_exp_f32_e32 v32, v32
	v_exp_f32_e32 v33, v33
	v_pk_add_f32 v[36:37], v[36:37], 1.0 op_sel_hi:[1,0]
	v_pk_add_f32 v[40:41], v[40:41], 1.0 op_sel_hi:[1,0]
	v_rcp_f32_e32 v34, v34
	v_rcp_f32_e32 v35, v35
	v_rcp_f32_e32 v40, v40
	v_rcp_f32_e32 v41, v41
	v_rcp_f32_e32 v36, v36
	v_rcp_f32_e32 v37, v37
	v_pk_add_f32 v[32:33], v[32:33], 1.0 op_sel_hi:[1,0]
	v_pk_mul_f32 v[20:21], v[20:21], v[38:39] op_sel_hi:[1,0]
	v_rcp_f32_e32 v32, v32
	v_rcp_f32_e32 v33, v33
	v_pk_mul_f32 v[28:29], v[28:29], v[34:35]
	v_add_u32_e32 v42, 0xa0, v180
	v_pk_mul_f32 v[18:19], v[18:19], v[38:39] op_sel_hi:[1,0]
	v_pk_mul_f32 v[16:17], v[16:17], v[38:39] op_sel_hi:[1,0]
	v_pk_mul_f32 v[20:21], v[20:21], v[28:29]
	v_pk_mul_f32 v[24:25], v[24:25], v[40:41]
	v_pk_mul_f32 v[26:27], v[26:27], v[36:37]
	v_pk_mul_f32 v[22:23], v[22:23], v[38:39] op_sel_hi:[1,0]
	v_pk_mul_f32 v[26:27], v[18:19], v[26:27]
	v_pk_mul_f32 v[18:19], v[16:17], v[24:25]
	v_cvt_pk_bf16_f32 v16, v20, v21
	v_mad_i64_i32 v[20:21], s[6:7], v42, s97, v[112:113]
	v_pk_mul_f32 v[30:31], v[30:31], v[32:33]
	v_lshl_add_u64 v[20:21], v[20:21], 0, s[42:43]
	v_pk_mul_f32 v[22:23], v[22:23], v[30:31]
	v_lshl_add_u64 v[20:21], v[20:21], 0, s[30:31]
	v_cvt_pk_bf16_f32 v17, v22, v23
	v_cvt_pk_bf16_f32 v18, v18, v19
	v_cvt_pk_bf16_f32 v19, v26, v27
	v_lshl_add_u64 v[20:21], v[20:21], 0, v[138:139]
	global_store_dwordx4 v[20:21], v[16:19], off
	s_nop 1
	v_mov_b32_e32 v16, v39
	v_pk_mul_f32 v[12:13], v[12:13], v[16:17] op_sel_hi:[1,0]
	v_pk_mul_f32 v[10:11], v[10:11], v[16:17] op_sel_hi:[1,0]
	v_pk_mul_f32 v[8:9], v[8:9], v[16:17] op_sel_hi:[1,0]
	v_pk_mul_f32 v[20:21], v[12:13], s[10:11] op_sel_hi:[1,0]
	v_pk_mul_f32 v[22:23], v[10:11], s[10:11] op_sel_hi:[1,0]
	v_pk_mul_f32 v[24:25], v[8:9], s[10:11] op_sel_hi:[1,0]
	v_exp_f32_e32 v20, v20
	v_exp_f32_e32 v21, v21
	v_pk_mul_f32 v[14:15], v[14:15], v[16:17] op_sel_hi:[1,0]
	v_exp_f32_e32 v24, v24
	v_exp_f32_e32 v25, v25
	v_exp_f32_e32 v22, v22
	v_exp_f32_e32 v23, v23
	v_pk_mul_f32 v[18:19], v[14:15], s[10:11] op_sel_hi:[1,0]
	v_pk_add_f32 v[20:21], v[20:21], 1.0 op_sel_hi:[1,0]
	v_exp_f32_e32 v18, v18
	v_exp_f32_e32 v19, v19
	v_pk_add_f32 v[22:23], v[22:23], 1.0 op_sel_hi:[1,0]
	v_pk_add_f32 v[24:25], v[24:25], 1.0 op_sel_hi:[1,0]
	v_rcp_f32_e32 v20, v20
	v_rcp_f32_e32 v21, v21
	v_rcp_f32_e32 v24, v24
	v_rcp_f32_e32 v25, v25
	v_rcp_f32_e32 v22, v22
	v_rcp_f32_e32 v23, v23
	v_pk_add_f32 v[18:19], v[18:19], 1.0 op_sel_hi:[1,0]
	v_pk_mul_f32 v[6:7], v[6:7], v[16:17] op_sel_hi:[1,0]
	v_rcp_f32_e32 v18, v18
	v_rcp_f32_e32 v19, v19
	v_pk_mul_f32 v[4:5], v[4:5], v[16:17] op_sel_hi:[1,0]
	v_add_u32_e32 v17, 0xb0, v180
	v_pk_mul_f32 v[12:13], v[12:13], v[20:21]
	v_pk_mul_f32 v[2:3], v[2:3], v[16:17] op_sel_hi:[1,0]
	v_pk_mul_f32 v[0:1], v[0:1], v[16:17] op_sel_hi:[1,0]
	v_pk_mul_f32 v[4:5], v[4:5], v[12:13]
	v_pk_mul_f32 v[8:9], v[8:9], v[24:25]
	v_pk_mul_f32 v[10:11], v[10:11], v[22:23]
	v_pk_mul_f32 v[14:15], v[14:15], v[18:19]
	v_pk_mul_f32 v[10:11], v[2:3], v[10:11]
	v_pk_mul_f32 v[2:3], v[0:1], v[8:9]
	v_cvt_pk_bf16_f32 v0, v4, v5
	v_mad_i64_i32 v[4:5], s[6:7], v17, s97, v[112:113]
	v_lshl_add_u64 v[4:5], v[4:5], 0, s[42:43]
	v_pk_mul_f32 v[6:7], v[6:7], v[14:15]
	v_lshl_add_u64 v[4:5], v[4:5], 0, s[30:31]
	v_cvt_pk_bf16_f32 v1, v6, v7
	v_cvt_pk_bf16_f32 v2, v2, v3
	v_cvt_pk_bf16_f32 v3, v10, v11
	v_lshl_add_u64 v[4:5], v[4:5], 0, v[138:139]
	global_store_dwordx4 v[4:5], v[0:3], off
	s_cbranch_vccnz .LBB0_807
	s_and_saveexec_b64 s[40:41], s[38:39]
	s_cbranch_execz .LBB0_823
	s_waitcnt vmcnt(8)
	v_pk_add_f32 v[0:1], v[158:159], v[162:163]
	v_pk_add_f32 v[2:3], v[156:157], v[160:161]
	v_pk_add_f32 v[0:1], v[150:151], v[0:1]
	v_pk_add_f32 v[2:3], v[148:149], v[2:3]
	v_pk_add_f32 v[0:1], v[142:143], v[0:1]
	v_pk_add_f32 v[2:3], v[140:141], v[2:3]
	v_pk_add_f32 v[0:1], v[154:155], v[0:1]
	v_pk_add_f32 v[2:3], v[152:153], v[2:3]
	v_pk_add_f32 v[0:1], v[146:147], v[0:1]
	v_pk_add_f32 v[2:3], v[144:145], v[2:3]
	v_pk_add_f32 v[0:1], v[134:135], v[0:1]
	v_pk_add_f32 v[2:3], v[132:133], v[2:3]
	v_pk_add_f32 v[0:1], v[130:131], v[0:1]
	v_pk_add_f32 v[2:3], v[128:129], v[2:3]
	s_lshl_b32 s6, s77, 10
	v_pk_mov_b32 v[4:5], v[2:3], v[0:1] op_sel:[1,0]
	v_mov_b32_e32 v3, v1
	v_pk_add_f32 v[0:1], v[4:5], v[2:3]
	s_and_b32 s6, s6, 0x400
	v_add_f32_e32 v0, v0, v1
	v_fmamk_f32 v0, v0, 0x3a000000, v237
	v_rsq_f32_e32 v0, v0
	v_add_u32_e32 v1, s6, v178
	ds_write_b32 v1, v0
